# GEMM unit order: workgroups owning a split-K sample slice run it before their main unit (G2/G4)
# speedup vs baseline: 1.0011x; 1.0011x over previous
.LBB0_799:
	s_lshl_b32 s31, 64, s22
	s_lshl_b32 s34, s8, s71
	s_load_dword s32, s[0:1], 0xe8
	s_waitcnt lgkmcnt(0)
	s_cmp_lg_u32 s32, s31
	s_cselect_b32 s32, 0, s32
	s_cmp_ge_u32 s26, s34
	s_cselect_b32 s32, 0, s32
	s_add_i32 s26, s26, s32
	s_sub_i32 s3, s26, s31
	s_sub_i32 s2, s3, s34
	s_cmp_ge_i32 s26, s31
	s_cselect_b64 s[6:7], -1, 0
	s_cmp_lt_i32 s3, s34
	s_cselect_b64 s[10:11], -1, 0
	s_cmp_ge_i32 s3, s34
	s_cselect_b64 s[4:5], -1, 0
	s_ashr_i32 s13, s3, s71
	s_mov_b64 s[8:9], -1
	s_and_b64 vcc, exec, s[6:7]
	s_cbranch_vccz .LBB0_801
	s_lshr_b32 s3, s13, s22
	s_add_i32 s3, s3, 64
	s_and_b64 s[8:9], s[10:11], exec
	s_cselect_b32 s36, s3, s2
	s_mov_b64 s[8:9], 0

; __device__ __forceinline__ int tidx() { int t = threadIdx.x; asm volatile("" : "+v"(t)); return t; }
; #define PG8_STAGE(bufoff, gbase, voff) do { _Pragma("unroll") for (int _i = 0; _i < 2; ++_i) \
;         __builtin_amdgcn_global_load_lds((const unsigned*)((const char*)(gbase) + (voff)[_i]), (LAS unsigned*)(lds + (bufoff) + ldsw + _i * 8192), 16, 0, 0); } while (0)
; #define PG8_BAR __builtin_amdgcn_s_barrier()
; template <class Epi, class Sched>
; __device__ __forceinline__ void gemm_phase(LAS unsigned char* lds, const Gemm g, const Sched& S, const Epi& E) {
;     const int tid = tidx(), wid = __builtin_amdgcn_readfirstlane(tid >> 6), lane = tid & 63, wr = wid >> 2, wc = wid & 3, fr = lane & 15, fq = lane >> 4;
;     const int K = g.K;
;     unsigned voffA[2], voffB[2];
; #pragma unroll
;     for (int i = 0; i < 2; ++i) { int R, C; stage_rc(tid * 16 + i * 8192, R, C); const int Rb = E.perm() ? ((R & ~31) + perm32(R & 31)) : R;
;         voffA[i] = (unsigned)(R * K + C) * 2u; voffB[i] = (unsigned)(Rb * K + C) * 2u; }
;     const size_t kstep = (size_t)(BK * 2);
;     const size_t hstep = (size_t)HALF * K * 2;
;     const size_t tstep = 2 * hstep;
;     const unsigned ldsw = (unsigned)wid * 1024u;
;     const int aoff = lds_byte(wr * 64 + fr, fq * 8), boff = lds_byte(wc * 32 + fr, fq * 8);
;     ...
;     Unit cur, nxt; int ui = 0;
;     if (!S.next(0, cur)) return;
;     f32x4 acc[2][2][4][2];
; #pragma unroll
;     for (int a = 0; a < 2; ++a)
; #pragma unroll
;         for (int b = 0; b < 2; ++b)
; #pragma unroll
;             for (int m = 0; m < 4; ++m)
; #pragma unroll
;                 for (int n = 0; n < 2; ++n) acc[a][b][m][n] = (f32x4){0.f, 0.f, 0.f, 0.f};
;     f16x8 At[4][2], B0[2][2], B1[2][2];
;     const char* cA = (const char*)g.A + (size_t)cur.pm * tstep + (size_t)(cur.k0 < 0 ? -1 - cur.k0 : cur.k0) * kstep; const char* cB = (const char*)g.Bt + (size_t)cur.pn * tstep + (size_t)(cur.k0 < 0 ? -1 - cur.k0 : cur.k0) * kstep;
;     S.a_ready(cur);
;     PG8_STAGE(PG8_SB(0, 0), cB, voffB); PG8_STAGE(PG8_SA(0, 0), cA, voffA); PG8_STAGE(PG8_SB(0, 1), cB + hstep, voffB); PG8_STAGE(PG8_SA(0, 1), cA + hstep, voffA);
;     if (wr == 1) PG8_BAR;
;     PG8_WAIT_V(4); PG8_BAR;
;     PG8_STAGE(PG8_SB(1, 0), cB + kstep, voffB); PG8_STAGE(PG8_SA(1, 0), cA + kstep, voffA); PG8_STAGE(PG8_SB(1, 1), cB + hstep + kstep, voffB);
;     PG8_WAIT_V(6); PG8_BAR;
.LBB0_813:
	s_lshl_b32 s13, s13, 5
	s_and_b32 s89, s13, 0x60
	s_not_b32 s88, s40
	s_lshl_b32 s12, s2, 13
	s_lshl_b32 s13, s89, 7
	s_and_b64 s[10:11], s[10:11], exec
	s_cselect_b32 s77, s73, s72
	s_add_i32 m0, s82, 0x18000
	v_lshl_add_u64 v[10:11], v[10:11], 0, s[90:91]
	s_waitcnt vmcnt(4)
	s_barrier
	global_load_lds_dwordx4 v[10:11], off
	v_lshl_add_u64 v[8:9], v[8:9], 0, s[90:91]
	s_add_i32 m0, s82, 0x1a000
	s_add_i32 s94, s82, 0x8000
	global_load_lds_dwordx4 v[8:9], off
	v_lshl_add_u64 v[6:7], v[6:7], 0, s[90:91]
	s_mov_b32 m0, s94
	s_add_i32 s95, s82, 0xa000
	global_load_lds_dwordx4 v[6:7], off
	v_lshl_add_u64 v[4:5], v[4:5], 0, s[90:91]
	s_mov_b32 m0, s95
	v_lshl_add_u64 v[2:3], v[2:3], 0, s[90:91]
	global_load_lds_dwordx4 v[4:5], off
	s_add_i32 m0, s82, 0x1c000
	v_lshl_add_u64 v[0:1], v[0:1], 0, s[90:91]
	global_load_lds_dwordx4 v[2:3], off
	s_add_i32 m0, s82, 0x1e000
	s_lshl_b32 s80, 1, s22
	global_load_lds_dwordx4 v[0:1], off
	v_bfe_u32 v1, v12, 4, 2
	v_and_b32_e32 v0, 15, v12
	v_lshlrev_b32_e32 v2, 4, v1
	v_lshl_or_b32 v139, s2, 6, v0
	v_lshl_or_b32 v0, v0, 6, v2
	v_lshlrev_b32_e32 v2, 2, v12
	v_and_b32_e32 v2, 32, v2
	v_bitop3_b32 v3, v0, s12, v2 bitop3:0xde
	v_bitop3_b32 v159, v0, s13, v2 bitop3:0xde
	s_lshl_b32 s2, -1, s22
	v_add_u32_e32 v0, v19, v16
	s_waitcnt vmcnt(6)
	s_not_b32 s81, s2
	s_lshl_b64 s[10:11], s[54:55], 16
	v_add_lshl_u32 v16, v0, v18, 1
	v_add_u32_e32 v0, v15, v13
	s_sub_u32 s58, 0, s10
	v_lshl_add_u64 v[140:141], s[44:45], 0, v[16:17]
	v_add_lshl_u32 v16, v0, v14, 1
	v_lshlrev_b32_e32 v158, 3, v1
	v_lshlrev_b32_e32 v160, 2, v1
	s_subb_u32 s59, 0, s11
	v_lshl_add_u64 v[142:143], s[44:45], 0, v[16:17]
	s_mov_b32 s45, 0
	s_sub_i32 s26, s26, s32
	v_add_u32_e32 v161, 0, v3
	s_barrier
	s_branch .LBB0_815

; template <class Epi, class Sched>
; __device__ __forceinline__ void gemm_phase(LAS unsigned char* lds, const Gemm g, const Sched& S, const Epi& E) {
;     ...
;         const bool has_next = S.next(ui + 1, nxt);
;         const char* nA = has_next ? (const char*)g.A + (size_t)nxt.pm * tstep + (size_t)(nxt.k0 < 0 ? -1 - nxt.k0 : nxt.k0) * kstep : cA; const char* nB = has_next ? (const char*)g.Bt + (size_t)nxt.pn * tstep + (size_t)(nxt.k0 < 0 ? -1 - nxt.k0 : nxt.k0) * kstep : cB;
.LBB0_815:
	s_load_dwordx2 s[10:11], s[0:1], 0xe8
	s_add_i32 s45, s45, 1
	s_mov_b64 s[40:41], -1
	s_waitcnt lgkmcnt(0)
	s_mul_i32 s62, s45, s10
	s_add_i32 s62, s62, s26
	s_add_i32 s62, s62, s32
	s_cmp_eq_u32 s45, 1
	s_cselect_b32 s2, s26, s62
	s_cmp_lg_u32 s32, 0
	s_cselect_b32 s62, s2, s62
	s_sub_i32 s2, s62, s31
	s_sub_i32 s64, s2, s34
	s_cmp_ge_i32 s62, s31
	s_cselect_b64 s[12:13], -1, 0
	s_cmp_lt_i32 s2, s34
	s_cselect_b64 s[10:11], -1, 0
	s_ashr_i32 s63, s2, s23
	s_and_b64 vcc, exec, s[12:13]
	s_cbranch_vccz .LBB0_817
	s_lshr_b32 s2, s63, s22
	s_add_i32 s2, s2, 64
	s_and_b64 s[40:41], s[10:11], exec
	s_cselect_b32 s2, s2, s64
	s_mov_b64 s[40:41], 0
